# v66 + prologue hyena-filter MLP: hidden-layer 2/3 weights loaded once per wave into 128 VGPRs, matvec loops unrolled over them (no per-position weight reloads)
# speedup vs baseline: 1.0140x; 1.0115x over previous
; #define GAS __attribute__((address_space(1)))
; __device__ __forceinline__ void pro_a(Frame& F, CArgs a, unsigned long long& tm_acc) {
;     ...
;         if (F.blk < DEPTH * 36) {
;             const int it = F.blk; const int l = it / 36, grp = it % 36; const bool isc = grp >= 32; const int L = isc ? CTXL : SEQ, p0 = (isc ? grp - 32 : grp) * 64;
;             __syncthreads();
;             { int _t = F.tid; asm volatile("" : "+v"(_t)); F.tid = _t; F.lane = _t & 63; F.wave = __builtin_amdgcn_readfirstlane(_t >> 6); }
;             for (int pp = 0; pp < 8; ++pp) {
;                 const int pos = p0 + F.wave * 8 + pp;
;                 const float t = (float)pos / (float)(L - 1);
;                 const float w = 6.2831853071795862f * (float)pos / (float)L;
;                 float zf = 0.f;
;                 if (F.lane == 0) zf = t;
;                 else if (F.lane < 33) { const int bi = (F.lane - 1) & 15; const float f = 1e-4f + (float)bi * ((15.0f - 1e-4f) / 15.0f); const float ang = f * w; zf = F.lane <= 16 ? cosf(ang) : -sinf(ang); }
;                 float h = ((const GAS float*)a->in[I_FB1])[l * 64 + F.lane];
;                 for (int i = 0; i < 33; ++i) h += __shfl(zf, i) * ((const GAS float*)a->in[I_FW1])[((size_t)l * 33 + i) * 64 + F.lane];
;                 h = sinf(((const GAS float*)a->in[I_FF1])[l * 64 + F.lane] * h);
;                 float h2 = ((const GAS float*)a->in[I_FB2])[l * 64 + F.lane];
;                 for (int i = 0; i < 64; ++i) h2 += __shfl(h, i) * ((const GAS float*)a->in[I_FW2])[((size_t)l * 64 + i) * 64 + F.lane];
.LBB0_207:
	s_or_b64 exec, exec, s[4:5]
	s_cmpk_lt_i32 s2, 0x90
	s_cbranch_scc0 .LBB0_270
	s_mul_hi_i32 s4, s2, 0x38e38e39
	s_lshr_b32 s5, s4, 31
	s_ashr_i32 s4, s4, 3
	s_barrier
	s_load_dwordx16 s[12:27], s[0:1], 0x60
	s_add_i32 s38, s4, s5
	s_waitcnt vmcnt(22)
	v_and_b32_e32 v6, 63, v0
	v_lshl_or_b32 v2, s38, 6, v6
	v_ashrrev_i32_e32 v3, 31, v2
	v_lshlrev_b64 v[2:3], 2, v[2:3]
	s_load_dwordx2 s[4:5], s[0:1], 0xa0
	s_waitcnt lgkmcnt(0)
	v_lshl_add_u64 v[4:5], s[14:15], 0, v[2:3]
	global_load_dword v12, v[4:5], off
	v_lshl_add_u64 v[4:5], s[16:17], 0, v[2:3]
	global_load_dword v13, v[4:5], off
	v_lshl_add_u64 v[4:5], s[20:21], 0, v[2:3]
	global_load_dword v14, v[4:5], off
	v_lshl_add_u64 v[4:5], s[22:23], 0, v[2:3]
	global_load_dword v15, v[4:5], off
	v_lshl_add_u64 v[4:5], s[26:27], 0, v[2:3]
	v_lshl_add_u64 v[2:3], s[4:5], 0, v[2:3]
	global_load_dword v16, v[4:5], off
	global_load_dword v17, v[2:3], off
	s_mul_i32 s4, s38, 36
	s_sub_i32 s4, s2, s4
	s_lshl_b32 s6, s4, 6
	s_add_i32 s7, s6, 0xfffff800
	s_cmp_gt_i32 s4, 31
	s_cselect_b64 s[16:17], -1, 0
	s_movk_i32 s8, 0x100
	s_and_b64 s[4:5], s[16:17], exec
	s_cselect_b32 s44, s8, 0x800
	s_cselect_b32 s45, s7, s6
	s_add_i32 s4, s44, -1
	v_cvt_f32_u32_e32 v1, s4
	v_readfirstlane_b32 s4, v0
	s_ashr_i32 s6, s4, 6
	s_ashr_i32 s39, s38, 31
	s_lshl_b32 s46, s6, 3
	v_mbcnt_lo_u32_b32 v2, -1, 0
	s_lshl_b32 s6, s6, 11
	s_lshl_b64 s[10:11], s[38:39], 14
	s_add_i32 s46, s46, s45
	v_mbcnt_hi_u32_b32 v3, -1, v2
	s_add_i32 s6, s6, 0
	v_add_u32_e32 v4, -1, v0
	s_mul_i32 s15, s38, 0x2100
	v_and_b32_e32 v4, 15, v4
	v_lshlrev_b32_e32 v3, 2, v3
	s_mul_hi_i32 s14, s38, 0x2100
	s_add_u32 s12, s12, s15
	s_waitcnt vmcnt(25)
	v_cvt_f32_u32_e32 v18, s44
	v_lshlrev_b32_e32 v2, 2, v6
	v_cvt_f32_ubyte0_e32 v4, v4
	v_mov_b32_e32 v20, 0x38d1b717
	v_and_b32_e32 v21, 0x100, v3
	v_mov_b32_e32 v3, 0
	s_addc_u32 s13, s13, s14
	v_add_u32_e32 v19, s6, v2
	v_fmac_f32_e32 v20, 0x3f7fff90, v4
	v_lshl_add_u64 v[4:5], s[12:13], 0, v[2:3]
	v_or_b32_e32 v2, s10, v2
	s_mov_b64 s[12:13], 0xa00
	v_or_b32_e32 v8, 0x700, v2
	v_mov_b32_e32 v9, s11
	s_mov_b32 s47, 0
	v_cmp_ne_u32_e64 s[4:5], 0, v6
	v_cmp_gt_u32_e64 s[6:7], 33, v6
	v_cmp_lt_u32_e64 s[8:9], 16, v6
	v_lshl_add_u64 v[4:5], v[4:5], 0, s[12:13]
	v_lshl_add_u64 v[6:7], s[18:19], 0, v[8:9]
	v_lshl_add_u64 v[8:9], s[24:25], 0, v[8:9]
	s_brev_b32 s48, 18
	s_mov_b32 s49, 0xfe5163ab
	s_mov_b32 s50, 0x3c439041
	s_mov_b32 s51, 0xdb629599
	s_mov_b32 s52, 0xf534ddc0
	s_mov_b32 s53, 0xfc2757d1
	s_mov_b32 s54, 0x4e441529
	s_mov_b32 s55, 0xa2f9836e
	s_mov_b32 s56, 0x3fc90fda
	s_mov_b32 s57, 0x3f22f983
	s_mov_b32 s58, 0xbfc90fda
	s_waitcnt vmcnt(24)
	v_mov_b32_e32 v22, 0x3c0881c4
	v_mov_b32_e32 v23, 0xbab64f3b
	s_brev_b32 s59, 1
	s_movk_i32 s60, 0x1f8
	s_mov_b64 s[18:19], 0xb00
	s_mov_b64 s[20:21], 0x800
	v_not_b32_e32 v24, 63
	v_not_b32_e32 v25, 31
	s_waitcnt vmcnt(23)
	v_mov_b32_e32 v26, 0xffc00000
	v_mov_b32_e32 v27, 0x7fc00000
	v_mov_b64_e32 v[10:11], v[6:7]
	global_load_dword v102, v[10:11], off offset:-1792
	global_load_dword v103, v[10:11], off offset:-1536
	global_load_dword v104, v[10:11], off offset:-1280
	global_load_dword v105, v[10:11], off offset:-1024
	global_load_dword v106, v[10:11], off offset:-768
	global_load_dword v107, v[10:11], off offset:-512
	global_load_dword v108, v[10:11], off offset:-256
	global_load_dword v109, v[10:11], off
	v_lshl_add_u64 v[10:11], v[10:11], 0, s[20:21]
	global_load_dword v110, v[10:11], off offset:-1792
	global_load_dword v111, v[10:11], off offset:-1536
	global_load_dword v112, v[10:11], off offset:-1280
	global_load_dword v113, v[10:11], off offset:-1024
	global_load_dword v114, v[10:11], off offset:-768
	global_load_dword v115, v[10:11], off offset:-512
	global_load_dword v116, v[10:11], off offset:-256
	global_load_dword v117, v[10:11], off
	v_lshl_add_u64 v[10:11], v[10:11], 0, s[20:21]
	global_load_dword v118, v[10:11], off offset:-1792
	global_load_dword v119, v[10:11], off offset:-1536
	global_load_dword v120, v[10:11], off offset:-1280
	global_load_dword v121, v[10:11], off offset:-1024
	global_load_dword v122, v[10:11], off offset:-768
	global_load_dword v123, v[10:11], off offset:-512
	global_load_dword v124, v[10:11], off offset:-256
	global_load_dword v125, v[10:11], off
	v_lshl_add_u64 v[10:11], v[10:11], 0, s[20:21]
	global_load_dword v126, v[10:11], off offset:-1792
	global_load_dword v127, v[10:11], off offset:-1536
	global_load_dword v128, v[10:11], off offset:-1280
	global_load_dword v129, v[10:11], off offset:-1024
	global_load_dword v130, v[10:11], off offset:-768
	global_load_dword v131, v[10:11], off offset:-512
	global_load_dword v132, v[10:11], off offset:-256
	global_load_dword v133, v[10:11], off
	v_lshl_add_u64 v[10:11], v[10:11], 0, s[20:21]
	global_load_dword v134, v[10:11], off offset:-1792
	global_load_dword v135, v[10:11], off offset:-1536
	global_load_dword v136, v[10:11], off offset:-1280
	global_load_dword v137, v[10:11], off offset:-1024
	global_load_dword v138, v[10:11], off offset:-768
	global_load_dword v139, v[10:11], off offset:-512
; #define GAS __attribute__((address_space(1)))
; __device__ __forceinline__ void pro_a(Frame& F, CArgs a, unsigned long long& tm_acc) {
;     ...
;                 float h2 = ((const GAS float*)a->in[I_FB2])[l * 64 + F.lane];
;                 for (int i = 0; i < 64; ++i) h2 += __shfl(h, i) * ((const GAS float*)a->in[I_FW2])[((size_t)l * 64 + i) * 64 + F.lane];
;                 h2 = sinf(((const GAS float*)a->in[I_FF2])[l * 64 + F.lane] * h2);
;                 float h3 = ((const GAS float*)a->in[I_FB3])[l * 64 + F.lane];
;                 for (int i = 0; i < 64; ++i) h3 += __shfl(h2, i) * ((const GAS float*)a->in[I_FW3])[((size_t)l * 64 + i) * 64 + F.lane];
	global_load_dword v140, v[10:11], off offset:-256
	global_load_dword v141, v[10:11], off
	v_lshl_add_u64 v[10:11], v[10:11], 0, s[20:21]
	global_load_dword v142, v[10:11], off offset:-1792
	global_load_dword v143, v[10:11], off offset:-1536
	global_load_dword v144, v[10:11], off offset:-1280
	global_load_dword v145, v[10:11], off offset:-1024
	global_load_dword v146, v[10:11], off offset:-768
	global_load_dword v147, v[10:11], off offset:-512
	global_load_dword v148, v[10:11], off offset:-256
	global_load_dword v149, v[10:11], off
	v_lshl_add_u64 v[10:11], v[10:11], 0, s[20:21]
	global_load_dword v150, v[10:11], off offset:-1792
	global_load_dword v151, v[10:11], off offset:-1536
	global_load_dword v152, v[10:11], off offset:-1280
	global_load_dword v153, v[10:11], off offset:-1024
	global_load_dword v154, v[10:11], off offset:-768
	global_load_dword v155, v[10:11], off offset:-512
	global_load_dword v156, v[10:11], off offset:-256
	global_load_dword v157, v[10:11], off
	v_lshl_add_u64 v[10:11], v[10:11], 0, s[20:21]
	global_load_dword v158, v[10:11], off offset:-1792
	global_load_dword v159, v[10:11], off offset:-1536
	global_load_dword v160, v[10:11], off offset:-1280
	global_load_dword v161, v[10:11], off offset:-1024
	global_load_dword v162, v[10:11], off offset:-768
	global_load_dword v163, v[10:11], off offset:-512
	global_load_dword v164, v[10:11], off offset:-256
	global_load_dword v165, v[10:11], off
	v_mov_b64_e32 v[10:11], v[8:9]
	global_load_dword v166, v[10:11], off offset:-1792
	global_load_dword v167, v[10:11], off offset:-1536
	global_load_dword v168, v[10:11], off offset:-1280
	global_load_dword v169, v[10:11], off offset:-1024
	global_load_dword v170, v[10:11], off offset:-768
	global_load_dword v171, v[10:11], off offset:-512
	global_load_dword v172, v[10:11], off offset:-256
	global_load_dword v173, v[10:11], off
	v_lshl_add_u64 v[10:11], v[10:11], 0, s[20:21]
	global_load_dword v174, v[10:11], off offset:-1792
	global_load_dword v175, v[10:11], off offset:-1536
	global_load_dword v176, v[10:11], off offset:-1280
	global_load_dword v177, v[10:11], off offset:-1024
	global_load_dword v178, v[10:11], off offset:-768
	global_load_dword v179, v[10:11], off offset:-512
	global_load_dword v180, v[10:11], off offset:-256
	global_load_dword v181, v[10:11], off
	v_lshl_add_u64 v[10:11], v[10:11], 0, s[20:21]
	global_load_dword v182, v[10:11], off offset:-1792
	global_load_dword v183, v[10:11], off offset:-1536
	global_load_dword v184, v[10:11], off offset:-1280
	global_load_dword v185, v[10:11], off offset:-1024
	global_load_dword v186, v[10:11], off offset:-768
	global_load_dword v187, v[10:11], off offset:-512
	global_load_dword v188, v[10:11], off offset:-256
	global_load_dword v189, v[10:11], off
	v_lshl_add_u64 v[10:11], v[10:11], 0, s[20:21]
	global_load_dword v190, v[10:11], off offset:-1792
	global_load_dword v191, v[10:11], off offset:-1536
	global_load_dword v192, v[10:11], off offset:-1280
	global_load_dword v193, v[10:11], off offset:-1024
	global_load_dword v194, v[10:11], off offset:-768
	global_load_dword v195, v[10:11], off offset:-512
	global_load_dword v196, v[10:11], off offset:-256
	global_load_dword v197, v[10:11], off
	v_lshl_add_u64 v[10:11], v[10:11], 0, s[20:21]
	global_load_dword v198, v[10:11], off offset:-1792
	global_load_dword v199, v[10:11], off offset:-1536
	global_load_dword v200, v[10:11], off offset:-1280
	global_load_dword v201, v[10:11], off offset:-1024
	global_load_dword v202, v[10:11], off offset:-768
	global_load_dword v203, v[10:11], off offset:-512
	global_load_dword v204, v[10:11], off offset:-256
	global_load_dword v205, v[10:11], off
	v_lshl_add_u64 v[10:11], v[10:11], 0, s[20:21]
	global_load_dword v206, v[10:11], off offset:-1792
	global_load_dword v207, v[10:11], off offset:-1536
	global_load_dword v208, v[10:11], off offset:-1280
	global_load_dword v209, v[10:11], off offset:-1024
	global_load_dword v210, v[10:11], off offset:-768
	global_load_dword v211, v[10:11], off offset:-512
	global_load_dword v212, v[10:11], off offset:-256
	global_load_dword v213, v[10:11], off
	v_lshl_add_u64 v[10:11], v[10:11], 0, s[20:21]
	global_load_dword v214, v[10:11], off offset:-1792
	global_load_dword v215, v[10:11], off offset:-1536
	global_load_dword v216, v[10:11], off offset:-1280
	global_load_dword v217, v[10:11], off offset:-1024
	global_load_dword v218, v[10:11], off offset:-768
	global_load_dword v219, v[10:11], off offset:-512
	global_load_dword v220, v[10:11], off offset:-256
	global_load_dword v221, v[10:11], off
	v_lshl_add_u64 v[10:11], v[10:11], 0, s[20:21]
	global_load_dword v222, v[10:11], off offset:-1792
	global_load_dword v223, v[10:11], off offset:-1536
	global_load_dword v224, v[10:11], off offset:-1280
	global_load_dword v225, v[10:11], off offset:-1024
	global_load_dword v226, v[10:11], off offset:-768
	global_load_dword v227, v[10:11], off offset:-512
	global_load_dword v228, v[10:11], off offset:-256
	global_load_dword v229, v[10:11], off
	s_waitcnt vmcnt(0)
	s_branch .LBB0_210

; #define GAS __attribute__((address_space(1)))
; __device__ __forceinline__ void pro_a(Frame& F, CArgs a, unsigned long long& tm_acc) {
;     ...
;                 float h = ((const GAS float*)a->in[I_FB1])[l * 64 + F.lane];
;                 for (int i = 0; i < 33; ++i) h += __shfl(zf, i) * ((const GAS float*)a->in[I_FW1])[((size_t)l * 33 + i) * 64 + F.lane];
;                 h = sinf(((const GAS float*)a->in[I_FF1])[l * 64 + F.lane] * h);
;                 float h2 = ((const GAS float*)a->in[I_FB2])[l * 64 + F.lane];
;                 for (int i = 0; i < 64; ++i) h2 += __shfl(h, i) * ((const GAS float*)a->in[I_FW2])[((size_t)l * 64 + i) * 64 + F.lane];
.LBB0_232:
	s_andn2_saveexec_b64 s[10:11], s[22:23]
	v_mul_f32_e64 v2, |v10|, s57
	v_rndne_f32_e32 v29, v2
	v_cvt_i32_f32_e32 v2, v29
	v_fma_f32 v28, v29, s58, |v10|
	v_fmac_f32_e32 v28, 0xb3a22168, v29
	v_fmac_f32_e32 v28, 0xa7c234c4, v29
	s_or_b64 exec, exec, s[10:11]
	v_mul_f32_e32 v29, v28, v28
	v_fmamk_f32 v30, v29, 0xb94c1982, v22
	v_fmaak_f32 v30, v29, v30, 0xbe2aaa9d
	v_mul_f32_e32 v30, v29, v30
	v_fmac_f32_e32 v28, v28, v30
	v_fmamk_f32 v30, v29, 0x37d75334, v23
	v_fmaak_f32 v30, v29, v30, 0x3d2aabf7
	v_fmaak_f32 v30, v29, v30, 0xbf000004
	v_fma_f32 v29, v29, v30, 1.0
	v_and_b32_e32 v30, 1, v2
	v_lshlrev_b32_e32 v2, 30, v2
	v_cmp_eq_u32_e32 vcc, 0, v30
	v_and_b32_e32 v2, 0x80000000, v2
	v_xor_b32_e32 v11, v11, v10
	v_cndmask_b32_e32 v28, v29, v28, vcc
	v_xor_b32_e32 v2, v11, v2
	v_xor_b32_e32 v2, v2, v28
	v_cmp_class_f32_e64 vcc, v10, s60
	s_mov_b32 s10, 0
	v_mov_b64_e32 v[10:11], v[6:7]
	v_cndmask_b32_e32 v2, v27, v2, vcc
	v_mov_b32_e32 v28, v14
	v_add_u32_e32 v37, 0, v21
	ds_bpermute_b32 v38, v37, v2
	ds_bpermute_b32 v39, v37, v2 offset:4
	ds_bpermute_b32 v40, v37, v2 offset:8
	ds_bpermute_b32 v41, v37, v2 offset:12
	ds_bpermute_b32 v42, v37, v2 offset:16
	ds_bpermute_b32 v43, v37, v2 offset:20
	ds_bpermute_b32 v44, v37, v2 offset:24
	ds_bpermute_b32 v37, v37, v2 offset:28
	s_waitcnt lgkmcnt(7)
	v_fmac_f32_e32 v28, v102, v38
	s_waitcnt lgkmcnt(6)
	v_fmac_f32_e32 v28, v103, v39
	s_waitcnt lgkmcnt(5)
	v_fmac_f32_e32 v28, v104, v40
	s_waitcnt lgkmcnt(4)
	v_fmac_f32_e32 v28, v105, v41
	s_waitcnt lgkmcnt(3)
	v_fmac_f32_e32 v28, v106, v42
	s_waitcnt lgkmcnt(2)
	v_fmac_f32_e32 v28, v107, v43
	s_waitcnt lgkmcnt(1)
	v_fmac_f32_e32 v28, v108, v44
	s_waitcnt lgkmcnt(0)
	v_fmac_f32_e32 v28, v109, v37
	v_add_u32_e32 v37, 32, v21
	ds_bpermute_b32 v38, v37, v2
	ds_bpermute_b32 v39, v37, v2 offset:4
	ds_bpermute_b32 v40, v37, v2 offset:8
	ds_bpermute_b32 v41, v37, v2 offset:12
	ds_bpermute_b32 v42, v37, v2 offset:16
	ds_bpermute_b32 v43, v37, v2 offset:20
	ds_bpermute_b32 v44, v37, v2 offset:24
	ds_bpermute_b32 v37, v37, v2 offset:28
	s_waitcnt lgkmcnt(7)
	v_fmac_f32_e32 v28, v110, v38
	s_waitcnt lgkmcnt(6)
	v_fmac_f32_e32 v28, v111, v39
	s_waitcnt lgkmcnt(5)
	v_fmac_f32_e32 v28, v112, v40
	s_waitcnt lgkmcnt(4)
	v_fmac_f32_e32 v28, v113, v41
	s_waitcnt lgkmcnt(3)
	v_fmac_f32_e32 v28, v114, v42
	s_waitcnt lgkmcnt(2)
	v_fmac_f32_e32 v28, v115, v43
	s_waitcnt lgkmcnt(1)
	v_fmac_f32_e32 v28, v116, v44
	s_waitcnt lgkmcnt(0)
	v_fmac_f32_e32 v28, v117, v37
	v_add_u32_e32 v37, 64, v21
	ds_bpermute_b32 v38, v37, v2
	ds_bpermute_b32 v39, v37, v2 offset:4
	ds_bpermute_b32 v40, v37, v2 offset:8
	ds_bpermute_b32 v41, v37, v2 offset:12
	ds_bpermute_b32 v42, v37, v2 offset:16
	ds_bpermute_b32 v43, v37, v2 offset:20
	ds_bpermute_b32 v44, v37, v2 offset:24
	ds_bpermute_b32 v37, v37, v2 offset:28
	s_waitcnt lgkmcnt(7)
	v_fmac_f32_e32 v28, v118, v38
	s_waitcnt lgkmcnt(6)
	v_fmac_f32_e32 v28, v119, v39
	s_waitcnt lgkmcnt(5)
	v_fmac_f32_e32 v28, v120, v40
	s_waitcnt lgkmcnt(4)
	v_fmac_f32_e32 v28, v121, v41
	s_waitcnt lgkmcnt(3)
	v_fmac_f32_e32 v28, v122, v42
	s_waitcnt lgkmcnt(2)
	v_fmac_f32_e32 v28, v123, v43
	s_waitcnt lgkmcnt(1)
	v_fmac_f32_e32 v28, v124, v44
	s_waitcnt lgkmcnt(0)
	v_fmac_f32_e32 v28, v125, v37
	v_add_u32_e32 v37, 0x60, v21
	ds_bpermute_b32 v38, v37, v2
	ds_bpermute_b32 v39, v37, v2 offset:4
	ds_bpermute_b32 v40, v37, v2 offset:8
	ds_bpermute_b32 v41, v37, v2 offset:12
	ds_bpermute_b32 v42, v37, v2 offset:16
	ds_bpermute_b32 v43, v37, v2 offset:20
	ds_bpermute_b32 v44, v37, v2 offset:24
	ds_bpermute_b32 v37, v37, v2 offset:28
	s_waitcnt lgkmcnt(7)
	v_fmac_f32_e32 v28, v126, v38
	s_waitcnt lgkmcnt(6)
	v_fmac_f32_e32 v28, v127, v39
	s_waitcnt lgkmcnt(5)
	v_fmac_f32_e32 v28, v128, v40
	s_waitcnt lgkmcnt(4)
	v_fmac_f32_e32 v28, v129, v41
	s_waitcnt lgkmcnt(3)
	v_fmac_f32_e32 v28, v130, v42
	s_waitcnt lgkmcnt(2)
	v_fmac_f32_e32 v28, v131, v43
	s_waitcnt lgkmcnt(1)
	v_fmac_f32_e32 v28, v132, v44
	s_waitcnt lgkmcnt(0)
	v_fmac_f32_e32 v28, v133, v37
	v_add_u32_e32 v37, 0x80, v21
	ds_bpermute_b32 v38, v37, v2
	ds_bpermute_b32 v39, v37, v2 offset:4
	ds_bpermute_b32 v40, v37, v2 offset:8
	ds_bpermute_b32 v41, v37, v2 offset:12
	ds_bpermute_b32 v42, v37, v2 offset:16
	ds_bpermute_b32 v43, v37, v2 offset:20
	ds_bpermute_b32 v44, v37, v2 offset:24
	ds_bpermute_b32 v37, v37, v2 offset:28
	s_waitcnt lgkmcnt(7)
	v_fmac_f32_e32 v28, v134, v38
	s_waitcnt lgkmcnt(6)
	v_fmac_f32_e32 v28, v135, v39
	s_waitcnt lgkmcnt(5)
	v_fmac_f32_e32 v28, v136, v40
	s_waitcnt lgkmcnt(4)
	v_fmac_f32_e32 v28, v137, v41
	s_waitcnt lgkmcnt(3)
	v_fmac_f32_e32 v28, v138, v42
	s_waitcnt lgkmcnt(2)
	v_fmac_f32_e32 v28, v139, v43
	s_waitcnt lgkmcnt(1)
	v_fmac_f32_e32 v28, v140, v44
	s_waitcnt lgkmcnt(0)
	v_fmac_f32_e32 v28, v141, v37
	v_add_u32_e32 v37, 0xa0, v21
	ds_bpermute_b32 v38, v37, v2
	ds_bpermute_b32 v39, v37, v2 offset:4
	ds_bpermute_b32 v40, v37, v2 offset:8
	ds_bpermute_b32 v41, v37, v2 offset:12
	ds_bpermute_b32 v42, v37, v2 offset:16
	ds_bpermute_b32 v43, v37, v2 offset:20
	ds_bpermute_b32 v44, v37, v2 offset:24
	ds_bpermute_b32 v37, v37, v2 offset:28
	s_waitcnt lgkmcnt(7)
	v_fmac_f32_e32 v28, v142, v38
	s_waitcnt lgkmcnt(6)
	v_fmac_f32_e32 v28, v143, v39
	s_waitcnt lgkmcnt(5)
	v_fmac_f32_e32 v28, v144, v40
	s_waitcnt lgkmcnt(4)
	v_fmac_f32_e32 v28, v145, v41
	s_waitcnt lgkmcnt(3)
	v_fmac_f32_e32 v28, v146, v42
	s_waitcnt lgkmcnt(2)
	v_fmac_f32_e32 v28, v147, v43
	s_waitcnt lgkmcnt(1)
	v_fmac_f32_e32 v28, v148, v44
	s_waitcnt lgkmcnt(0)
; #define GAS __attribute__((address_space(1)))
; __device__ __forceinline__ void pro_a(Frame& F, CArgs a, unsigned long long& tm_acc) {
;     ...
;                 for (int i = 0; i < 64; ++i) h2 += __shfl(h, i) * ((const GAS float*)a->in[I_FW2])[((size_t)l * 64 + i) * 64 + F.lane];
;                 h2 = sinf(((const GAS float*)a->in[I_FF2])[l * 64 + F.lane] * h2);
	v_fmac_f32_e32 v28, v149, v37
	v_add_u32_e32 v37, 0xc0, v21
	ds_bpermute_b32 v38, v37, v2
	ds_bpermute_b32 v39, v37, v2 offset:4
	ds_bpermute_b32 v40, v37, v2 offset:8
	ds_bpermute_b32 v41, v37, v2 offset:12
	ds_bpermute_b32 v42, v37, v2 offset:16
	ds_bpermute_b32 v43, v37, v2 offset:20
	ds_bpermute_b32 v44, v37, v2 offset:24
	ds_bpermute_b32 v37, v37, v2 offset:28
	s_waitcnt lgkmcnt(7)
	v_fmac_f32_e32 v28, v150, v38
	s_waitcnt lgkmcnt(6)
	v_fmac_f32_e32 v28, v151, v39
	s_waitcnt lgkmcnt(5)
	v_fmac_f32_e32 v28, v152, v40
	s_waitcnt lgkmcnt(4)
	v_fmac_f32_e32 v28, v153, v41
	s_waitcnt lgkmcnt(3)
	v_fmac_f32_e32 v28, v154, v42
	s_waitcnt lgkmcnt(2)
	v_fmac_f32_e32 v28, v155, v43
	s_waitcnt lgkmcnt(1)
	v_fmac_f32_e32 v28, v156, v44
	s_waitcnt lgkmcnt(0)
	v_fmac_f32_e32 v28, v157, v37
	v_add_u32_e32 v37, 0xe0, v21
	ds_bpermute_b32 v38, v37, v2
	ds_bpermute_b32 v39, v37, v2 offset:4
	ds_bpermute_b32 v40, v37, v2 offset:8
	ds_bpermute_b32 v41, v37, v2 offset:12
	ds_bpermute_b32 v42, v37, v2 offset:16
	ds_bpermute_b32 v43, v37, v2 offset:20
	ds_bpermute_b32 v44, v37, v2 offset:24
	ds_bpermute_b32 v37, v37, v2 offset:28
	s_waitcnt lgkmcnt(7)
	v_fmac_f32_e32 v28, v158, v38
	s_waitcnt lgkmcnt(6)
	v_fmac_f32_e32 v28, v159, v39
	s_waitcnt lgkmcnt(5)
	v_fmac_f32_e32 v28, v160, v40
	s_waitcnt lgkmcnt(4)
	v_fmac_f32_e32 v28, v161, v41
	s_waitcnt lgkmcnt(3)
	v_fmac_f32_e32 v28, v162, v42
	s_waitcnt lgkmcnt(2)
	v_fmac_f32_e32 v28, v163, v43
	s_waitcnt lgkmcnt(1)
	v_fmac_f32_e32 v28, v164, v44
	s_waitcnt lgkmcnt(0)
	v_fmac_f32_e32 v28, v165, v37
	v_mul_f32_e32 v10, v15, v28
	v_and_b32_e32 v11, 0x7fffffff, v10
	v_cmp_nlt_f32_e64 s[10:11], |v10|, s48
	s_and_saveexec_b64 s[12:13], s[10:11]
	s_xor_b64 s[22:23], exec, s[12:13]
	s_cbranch_execz .LBB0_238
	v_lshrrev_b32_e32 v2, 23, v11
	v_add_u32_e32 v2, 0xffffff88, v2
	v_cmp_lt_u32_e32 vcc, 63, v2
	s_nop 1
	v_cndmask_b32_e32 v28, 0, v24, vcc
	v_add_u32_e32 v2, v28, v2
	v_cmp_lt_u32_e64 s[10:11], 31, v2
	s_nop 1
	v_cndmask_b32_e64 v28, 0, v25, s[10:11]
	v_add_u32_e32 v2, v28, v2
	v_cmp_lt_u32_e64 s[12:13], 31, v2
	s_nop 1
	v_cndmask_b32_e64 v28, 0, v25, s[12:13]
	v_add_u32_e32 v42, v28, v2
	v_and_b32_e32 v2, 0x7fffff, v11
	v_or_b32_e32 v40, 0x800000, v2
	v_mad_u64_u32 v[28:29], s[14:15], v40, s49, 0
	v_mov_b32_e32 v2, v29
	v_mad_u64_u32 v[30:31], s[14:15], v40, s50, v[2:3]
	v_mov_b32_e32 v2, v31
	v_mad_u64_u32 v[32:33], s[14:15], v40, s51, v[2:3]
	v_mov_b32_e32 v2, v33
	v_mad_u64_u32 v[34:35], s[14:15], v40, s52, v[2:3]
	v_mov_b32_e32 v2, v35
	v_mad_u64_u32 v[36:37], s[14:15], v40, s53, v[2:3]
	v_mov_b32_e32 v2, v37
	v_mad_u64_u32 v[38:39], s[14:15], v40, s54, v[2:3]
	v_mov_b32_e32 v2, v39
	v_mad_u64_u32 v[40:41], s[14:15], v40, s55, v[2:3]
	v_cndmask_b32_e32 v29, v38, v34, vcc
	v_cndmask_b32_e32 v2, v40, v36, vcc
	v_cndmask_b32_e32 v33, v41, v38, vcc
	v_cndmask_b32_e64 v31, v2, v29, s[10:11]
	v_cndmask_b32_e64 v2, v33, v2, s[10:11]
	v_cndmask_b32_e32 v33, v36, v32, vcc
	v_cndmask_b32_e64 v29, v29, v33, s[10:11]
	v_cndmask_b32_e32 v30, v34, v30, vcc
	v_cndmask_b32_e64 v2, v2, v31, s[12:13]
	v_cndmask_b32_e64 v31, v31, v29, s[12:13]
	v_sub_u32_e32 v35, 32, v42
	v_cndmask_b32_e64 v33, v33, v30, s[10:11]
	v_alignbit_b32 v36, v2, v31, v35
	v_cmp_eq_u32_e64 s[14:15], 0, v42
	v_cndmask_b32_e64 v29, v29, v33, s[12:13]
	v_cndmask_b32_e32 v28, v32, v28, vcc
	v_cndmask_b32_e64 v2, v36, v2, s[14:15]
	v_alignbit_b32 v34, v31, v29, v35
	v_cndmask_b32_e64 v28, v30, v28, s[10:11]
	v_cndmask_b32_e64 v31, v34, v31, s[14:15]
	v_bfe_u32 v37, v2, 29, 1
	v_cndmask_b32_e64 v28, v33, v28, s[12:13]
	v_alignbit_b32 v34, v2, v31, 30
	v_sub_u32_e32 v38, 0, v37
	v_alignbit_b32 v30, v29, v28, v35
	v_xor_b32_e32 v34, v34, v38
	v_cndmask_b32_e64 v29, v30, v29, s[14:15]
	v_alignbit_b32 v30, v31, v29, 30
	v_ffbh_u32_e32 v31, v34
	v_min_u32_e32 v31, 32, v31
	v_alignbit_b32 v28, v29, v28, 30
	v_xor_b32_e32 v30, v30, v38
	v_sub_u32_e32 v32, 31, v31
	v_xor_b32_e32 v28, v28, v38
	v_alignbit_b32 v33, v34, v30, v32
	v_alignbit_b32 v28, v30, v28, v32
	v_alignbit_b32 v29, v33, v28, 9
	v_ffbh_u32_e32 v30, v29
	v_min_u32_e32 v30, 32, v30
	v_lshrrev_b32_e32 v36, 29, v2
	v_not_b32_e32 v32, v30
	v_alignbit_b32 v28, v29, v28, v32
	v_lshlrev_b32_e32 v29, 31, v36
	v_or_b32_e32 v32, 0x33000000, v29
	v_add_lshl_u32 v30, v30, v31, 23
	v_lshrrev_b32_e32 v28, 9, v28
	v_sub_u32_e32 v30, v32, v30
	v_or_b32_e32 v29, 0.5, v29
	v_lshlrev_b32_e32 v31, 23, v31
	v_or_b32_e32 v28, v30, v28
	v_lshrrev_b32_e32 v30, 9, v33
	v_sub_u32_e32 v29, v29, v31
	v_or_b32_e32 v29, v30, v29
	v_mul_f32_e32 v30, 0x3fc90fda, v29
	v_fma_f32 v31, v29, s56, -v30
	v_fmac_f32_e32 v31, 0x33a22168, v29
	v_fmac_f32_e32 v31, 0x3fc90fda, v28
	v_lshrrev_b32_e32 v2, 30, v2
	v_add_f32_e32 v28, v30, v31
	v_add_u32_e32 v2, v37, v2
; #define GAS __attribute__((address_space(1)))
; __device__ __forceinline__ void pro_a(Frame& F, CArgs a, unsigned long long& tm_acc) {
;     ...
;                 h2 = sinf(((const GAS float*)a->in[I_FF2])[l * 64 + F.lane] * h2);
;                 float h3 = ((const GAS float*)a->in[I_FB3])[l * 64 + F.lane];
;                 for (int i = 0; i < 64; ++i) h3 += __shfl(h2, i) * ((const GAS float*)a->in[I_FW3])[((size_t)l * 64 + i) * 64 + F.lane];
.LBB0_238:
	s_andn2_saveexec_b64 s[10:11], s[22:23]
	v_mul_f32_e64 v2, |v10|, s57
	v_rndne_f32_e32 v29, v2
	v_cvt_i32_f32_e32 v2, v29
	v_fma_f32 v28, v29, s58, |v10|
	v_fmac_f32_e32 v28, 0xb3a22168, v29
	v_fmac_f32_e32 v28, 0xa7c234c4, v29
	s_or_b64 exec, exec, s[10:11]
	v_mul_f32_e32 v29, v28, v28
	v_fmamk_f32 v30, v29, 0xb94c1982, v22
	v_fmaak_f32 v30, v29, v30, 0xbe2aaa9d
	v_mul_f32_e32 v30, v29, v30
	v_fmac_f32_e32 v28, v28, v30
	v_fmamk_f32 v30, v29, 0x37d75334, v23
	v_fmaak_f32 v30, v29, v30, 0x3d2aabf7
	v_fmaak_f32 v30, v29, v30, 0xbf000004
	v_fma_f32 v29, v29, v30, 1.0
	v_and_b32_e32 v30, 1, v2
	v_lshlrev_b32_e32 v2, 30, v2
	v_cmp_eq_u32_e32 vcc, 0, v30
	v_and_b32_e32 v2, 0x80000000, v2
	v_xor_b32_e32 v11, v11, v10
	v_cndmask_b32_e32 v28, v29, v28, vcc
	v_xor_b32_e32 v2, v11, v2
	v_xor_b32_e32 v2, v2, v28
	v_cmp_class_f32_e64 vcc, v10, s60
	s_mov_b32 s10, 0
	v_mov_b64_e32 v[10:11], v[8:9]
	v_cndmask_b32_e32 v2, v27, v2, vcc
	v_mov_b32_e32 v28, v16
	v_add_u32_e32 v37, 0, v21
	ds_bpermute_b32 v38, v37, v2
	ds_bpermute_b32 v39, v37, v2 offset:4
	ds_bpermute_b32 v40, v37, v2 offset:8
	ds_bpermute_b32 v41, v37, v2 offset:12
	ds_bpermute_b32 v42, v37, v2 offset:16
	ds_bpermute_b32 v43, v37, v2 offset:20
	ds_bpermute_b32 v44, v37, v2 offset:24
	ds_bpermute_b32 v37, v37, v2 offset:28
	s_waitcnt lgkmcnt(7)
	v_fmac_f32_e32 v28, v166, v38
	s_waitcnt lgkmcnt(6)
	v_fmac_f32_e32 v28, v167, v39
	s_waitcnt lgkmcnt(5)
	v_fmac_f32_e32 v28, v168, v40
	s_waitcnt lgkmcnt(4)
	v_fmac_f32_e32 v28, v169, v41
	s_waitcnt lgkmcnt(3)
	v_fmac_f32_e32 v28, v170, v42
	s_waitcnt lgkmcnt(2)
	v_fmac_f32_e32 v28, v171, v43
	s_waitcnt lgkmcnt(1)
	v_fmac_f32_e32 v28, v172, v44
	s_waitcnt lgkmcnt(0)
	v_fmac_f32_e32 v28, v173, v37
	v_add_u32_e32 v37, 32, v21
	ds_bpermute_b32 v38, v37, v2
	ds_bpermute_b32 v39, v37, v2 offset:4
	ds_bpermute_b32 v40, v37, v2 offset:8
	ds_bpermute_b32 v41, v37, v2 offset:12
	ds_bpermute_b32 v42, v37, v2 offset:16
	ds_bpermute_b32 v43, v37, v2 offset:20
	ds_bpermute_b32 v44, v37, v2 offset:24
	ds_bpermute_b32 v37, v37, v2 offset:28
	s_waitcnt lgkmcnt(7)
	v_fmac_f32_e32 v28, v174, v38
	s_waitcnt lgkmcnt(6)
	v_fmac_f32_e32 v28, v175, v39
	s_waitcnt lgkmcnt(5)
	v_fmac_f32_e32 v28, v176, v40
	s_waitcnt lgkmcnt(4)
	v_fmac_f32_e32 v28, v177, v41
	s_waitcnt lgkmcnt(3)
	v_fmac_f32_e32 v28, v178, v42
	s_waitcnt lgkmcnt(2)
	v_fmac_f32_e32 v28, v179, v43
	s_waitcnt lgkmcnt(1)
	v_fmac_f32_e32 v28, v180, v44
	s_waitcnt lgkmcnt(0)
	v_fmac_f32_e32 v28, v181, v37
	v_add_u32_e32 v37, 64, v21
	ds_bpermute_b32 v38, v37, v2
	ds_bpermute_b32 v39, v37, v2 offset:4
	ds_bpermute_b32 v40, v37, v2 offset:8
	ds_bpermute_b32 v41, v37, v2 offset:12
	ds_bpermute_b32 v42, v37, v2 offset:16
	ds_bpermute_b32 v43, v37, v2 offset:20
	ds_bpermute_b32 v44, v37, v2 offset:24
	ds_bpermute_b32 v37, v37, v2 offset:28
	s_waitcnt lgkmcnt(7)
	v_fmac_f32_e32 v28, v182, v38
	s_waitcnt lgkmcnt(6)
	v_fmac_f32_e32 v28, v183, v39
	s_waitcnt lgkmcnt(5)
	v_fmac_f32_e32 v28, v184, v40
	s_waitcnt lgkmcnt(4)
	v_fmac_f32_e32 v28, v185, v41
	s_waitcnt lgkmcnt(3)
	v_fmac_f32_e32 v28, v186, v42
	s_waitcnt lgkmcnt(2)
	v_fmac_f32_e32 v28, v187, v43
	s_waitcnt lgkmcnt(1)
	v_fmac_f32_e32 v28, v188, v44
	s_waitcnt lgkmcnt(0)
	v_fmac_f32_e32 v28, v189, v37
	v_add_u32_e32 v37, 0x60, v21
	ds_bpermute_b32 v38, v37, v2
	ds_bpermute_b32 v39, v37, v2 offset:4
	ds_bpermute_b32 v40, v37, v2 offset:8
	ds_bpermute_b32 v41, v37, v2 offset:12
	ds_bpermute_b32 v42, v37, v2 offset:16
	ds_bpermute_b32 v43, v37, v2 offset:20
	ds_bpermute_b32 v44, v37, v2 offset:24
	ds_bpermute_b32 v37, v37, v2 offset:28
	s_waitcnt lgkmcnt(7)
	v_fmac_f32_e32 v28, v190, v38
	s_waitcnt lgkmcnt(6)
	v_fmac_f32_e32 v28, v191, v39
	s_waitcnt lgkmcnt(5)
	v_fmac_f32_e32 v28, v192, v40
	s_waitcnt lgkmcnt(4)
	v_fmac_f32_e32 v28, v193, v41
	s_waitcnt lgkmcnt(3)
	v_fmac_f32_e32 v28, v194, v42
	s_waitcnt lgkmcnt(2)
	v_fmac_f32_e32 v28, v195, v43
	s_waitcnt lgkmcnt(1)
	v_fmac_f32_e32 v28, v196, v44
	s_waitcnt lgkmcnt(0)
	v_fmac_f32_e32 v28, v197, v37
	v_add_u32_e32 v37, 0x80, v21
	ds_bpermute_b32 v38, v37, v2
	ds_bpermute_b32 v39, v37, v2 offset:4
	ds_bpermute_b32 v40, v37, v2 offset:8
	ds_bpermute_b32 v41, v37, v2 offset:12
	ds_bpermute_b32 v42, v37, v2 offset:16
	ds_bpermute_b32 v43, v37, v2 offset:20
	ds_bpermute_b32 v44, v37, v2 offset:24
	ds_bpermute_b32 v37, v37, v2 offset:28
	s_waitcnt lgkmcnt(7)
	v_fmac_f32_e32 v28, v198, v38
	s_waitcnt lgkmcnt(6)
	v_fmac_f32_e32 v28, v199, v39
	s_waitcnt lgkmcnt(5)
	v_fmac_f32_e32 v28, v200, v40
	s_waitcnt lgkmcnt(4)
	v_fmac_f32_e32 v28, v201, v41
	s_waitcnt lgkmcnt(3)
	v_fmac_f32_e32 v28, v202, v42
	s_waitcnt lgkmcnt(2)
	v_fmac_f32_e32 v28, v203, v43
	s_waitcnt lgkmcnt(1)
	v_fmac_f32_e32 v28, v204, v44
	s_waitcnt lgkmcnt(0)
	v_fmac_f32_e32 v28, v205, v37
	v_add_u32_e32 v37, 0xa0, v21
	ds_bpermute_b32 v38, v37, v2
	ds_bpermute_b32 v39, v37, v2 offset:4
	ds_bpermute_b32 v40, v37, v2 offset:8
	ds_bpermute_b32 v41, v37, v2 offset:12
	ds_bpermute_b32 v42, v37, v2 offset:16
	ds_bpermute_b32 v43, v37, v2 offset:20
	ds_bpermute_b32 v44, v37, v2 offset:24
	ds_bpermute_b32 v37, v37, v2 offset:28
	s_waitcnt lgkmcnt(7)
; #define GAS __attribute__((address_space(1)))
; __device__ __forceinline__ void pro_a(Frame& F, CArgs a, unsigned long long& tm_acc) {
;     ...
;                 for (int i = 0; i < 64; ++i) h3 += __shfl(h2, i) * ((const GAS float*)a->in[I_FW3])[((size_t)l * 64 + i) * 64 + F.lane];
;                 h3 = sinf(((const GAS float*)a->in[I_FF3])[l * 64 + F.lane] * h3);
	v_fmac_f32_e32 v28, v206, v38
	s_waitcnt lgkmcnt(6)
	v_fmac_f32_e32 v28, v207, v39
	s_waitcnt lgkmcnt(5)
	v_fmac_f32_e32 v28, v208, v40
	s_waitcnt lgkmcnt(4)
	v_fmac_f32_e32 v28, v209, v41
	s_waitcnt lgkmcnt(3)
	v_fmac_f32_e32 v28, v210, v42
	s_waitcnt lgkmcnt(2)
	v_fmac_f32_e32 v28, v211, v43
	s_waitcnt lgkmcnt(1)
	v_fmac_f32_e32 v28, v212, v44
	s_waitcnt lgkmcnt(0)
	v_fmac_f32_e32 v28, v213, v37
	v_add_u32_e32 v37, 0xc0, v21
	ds_bpermute_b32 v38, v37, v2
	ds_bpermute_b32 v39, v37, v2 offset:4
	ds_bpermute_b32 v40, v37, v2 offset:8
	ds_bpermute_b32 v41, v37, v2 offset:12
	ds_bpermute_b32 v42, v37, v2 offset:16
	ds_bpermute_b32 v43, v37, v2 offset:20
	ds_bpermute_b32 v44, v37, v2 offset:24
	ds_bpermute_b32 v37, v37, v2 offset:28
	s_waitcnt lgkmcnt(7)
	v_fmac_f32_e32 v28, v214, v38
	s_waitcnt lgkmcnt(6)
	v_fmac_f32_e32 v28, v215, v39
	s_waitcnt lgkmcnt(5)
	v_fmac_f32_e32 v28, v216, v40
	s_waitcnt lgkmcnt(4)
	v_fmac_f32_e32 v28, v217, v41
	s_waitcnt lgkmcnt(3)
	v_fmac_f32_e32 v28, v218, v42
	s_waitcnt lgkmcnt(2)
	v_fmac_f32_e32 v28, v219, v43
	s_waitcnt lgkmcnt(1)
	v_fmac_f32_e32 v28, v220, v44
	s_waitcnt lgkmcnt(0)
	v_fmac_f32_e32 v28, v221, v37
	v_add_u32_e32 v37, 0xe0, v21
	ds_bpermute_b32 v38, v37, v2
	ds_bpermute_b32 v39, v37, v2 offset:4
	ds_bpermute_b32 v40, v37, v2 offset:8
	ds_bpermute_b32 v41, v37, v2 offset:12
	ds_bpermute_b32 v42, v37, v2 offset:16
	ds_bpermute_b32 v43, v37, v2 offset:20
	ds_bpermute_b32 v44, v37, v2 offset:24
	ds_bpermute_b32 v37, v37, v2 offset:28
	s_waitcnt lgkmcnt(7)
	v_fmac_f32_e32 v28, v222, v38
	s_waitcnt lgkmcnt(6)
	v_fmac_f32_e32 v28, v223, v39
	s_waitcnt lgkmcnt(5)
	v_fmac_f32_e32 v28, v224, v40
	s_waitcnt lgkmcnt(4)
	v_fmac_f32_e32 v28, v225, v41
	s_waitcnt lgkmcnt(3)
	v_fmac_f32_e32 v28, v226, v42
	s_waitcnt lgkmcnt(2)
	v_fmac_f32_e32 v28, v227, v43
	s_waitcnt lgkmcnt(1)
	v_fmac_f32_e32 v28, v228, v44
	s_waitcnt lgkmcnt(0)
	v_fmac_f32_e32 v28, v229, v37
	v_mul_f32_e32 v10, v17, v28
	v_and_b32_e32 v11, 0x7fffffff, v10
	v_cmp_nlt_f32_e64 s[10:11], |v10|, s48
	s_and_saveexec_b64 s[12:13], s[10:11]
	s_xor_b64 s[22:23], exec, s[12:13]
	s_cbranch_execz .LBB0_244
	v_lshrrev_b32_e32 v2, 23, v11
	v_add_u32_e32 v2, 0xffffff88, v2
	v_cmp_lt_u32_e32 vcc, 63, v2
	s_nop 1
	v_cndmask_b32_e32 v28, 0, v24, vcc
	v_add_u32_e32 v2, v28, v2
	v_cmp_lt_u32_e64 s[10:11], 31, v2
	s_nop 1
	v_cndmask_b32_e64 v28, 0, v25, s[10:11]
	v_add_u32_e32 v2, v28, v2
	v_cmp_lt_u32_e64 s[12:13], 31, v2
	s_nop 1
	v_cndmask_b32_e64 v28, 0, v25, s[12:13]
	v_add_u32_e32 v42, v28, v2
	v_and_b32_e32 v2, 0x7fffff, v11
	v_or_b32_e32 v40, 0x800000, v2
	v_mad_u64_u32 v[28:29], s[14:15], v40, s49, 0
	v_mov_b32_e32 v2, v29
	v_mad_u64_u32 v[30:31], s[14:15], v40, s50, v[2:3]
	v_mov_b32_e32 v2, v31
	v_mad_u64_u32 v[32:33], s[14:15], v40, s51, v[2:3]
	v_mov_b32_e32 v2, v33
	v_mad_u64_u32 v[34:35], s[14:15], v40, s52, v[2:3]
	v_mov_b32_e32 v2, v35
	v_mad_u64_u32 v[36:37], s[14:15], v40, s53, v[2:3]
	v_mov_b32_e32 v2, v37
	v_mad_u64_u32 v[38:39], s[14:15], v40, s54, v[2:3]
	v_mov_b32_e32 v2, v39
	v_mad_u64_u32 v[40:41], s[14:15], v40, s55, v[2:3]
	v_cndmask_b32_e32 v29, v38, v34, vcc
	v_cndmask_b32_e32 v2, v40, v36, vcc
	v_cndmask_b32_e32 v33, v41, v38, vcc
	v_cndmask_b32_e64 v31, v2, v29, s[10:11]
	v_cndmask_b32_e64 v2, v33, v2, s[10:11]
	v_cndmask_b32_e32 v33, v36, v32, vcc
	v_cndmask_b32_e64 v29, v29, v33, s[10:11]
	v_cndmask_b32_e32 v30, v34, v30, vcc
	v_cndmask_b32_e64 v2, v2, v31, s[12:13]
	v_cndmask_b32_e64 v31, v31, v29, s[12:13]
	v_sub_u32_e32 v35, 32, v42
	v_cndmask_b32_e64 v33, v33, v30, s[10:11]
	v_alignbit_b32 v36, v2, v31, v35
	v_cmp_eq_u32_e64 s[14:15], 0, v42
	v_cndmask_b32_e64 v29, v29, v33, s[12:13]
	v_cndmask_b32_e32 v28, v32, v28, vcc
	v_cndmask_b32_e64 v2, v36, v2, s[14:15]
	v_alignbit_b32 v34, v31, v29, v35
	v_cndmask_b32_e64 v28, v30, v28, s[10:11]
	v_cndmask_b32_e64 v31, v34, v31, s[14:15]
	v_bfe_u32 v37, v2, 29, 1
	v_cndmask_b32_e64 v28, v33, v28, s[12:13]
	v_alignbit_b32 v34, v2, v31, 30
	v_sub_u32_e32 v38, 0, v37
	v_alignbit_b32 v30, v29, v28, v35
	v_xor_b32_e32 v34, v34, v38
	v_cndmask_b32_e64 v29, v30, v29, s[14:15]
	v_alignbit_b32 v30, v31, v29, 30
	v_ffbh_u32_e32 v31, v34
	v_min_u32_e32 v31, 32, v31
	v_alignbit_b32 v28, v29, v28, 30
	v_xor_b32_e32 v30, v30, v38
	v_sub_u32_e32 v32, 31, v31
	v_xor_b32_e32 v28, v28, v38
	v_alignbit_b32 v33, v34, v30, v32
	v_alignbit_b32 v28, v30, v28, v32
	v_alignbit_b32 v29, v33, v28, 9
	v_ffbh_u32_e32 v30, v29
	v_min_u32_e32 v30, 32, v30
	v_lshrrev_b32_e32 v36, 29, v2
	v_not_b32_e32 v32, v30
	v_alignbit_b32 v28, v29, v28, v32
	v_lshlrev_b32_e32 v29, 31, v36
	v_or_b32_e32 v32, 0x33000000, v29
	v_add_lshl_u32 v30, v30, v31, 23
	v_lshrrev_b32_e32 v28, 9, v28
	v_sub_u32_e32 v30, v32, v30
	v_or_b32_e32 v29, 0.5, v29
	v_lshlrev_b32_e32 v31, 23, v31
	v_or_b32_e32 v28, v30, v28
	v_lshrrev_b32_e32 v30, 9, v33
	v_sub_u32_e32 v29, v29, v31
	v_or_b32_e32 v29, v30, v29
	v_mul_f32_e32 v30, 0x3fc90fda, v29
	v_fma_f32 v31, v29, s56, -v30
	v_fmac_f32_e32 v31, 0x33a22168, v29
	v_fmac_f32_e32 v31, 0x3fc90fda, v28
	v_lshrrev_b32_e32 v2, 30, v2
	v_add_f32_e32 v28, v30, v31
	v_add_u32_e32 v2, v37, v2
